# v47: W_down transposer pairs adjacent k-blocks per wave (whole 128B lines per wave) so the fixup->DOWN barrier also drops buffer_inv
# baseline (speedup 1.0000x reference)
; template <int MODE>
; __device__ __forceinline__ void transpose_item(const float* __restrict__ W, int K, int N, bf16_t* __restrict__ WT, int HH, float* scr, int item, int lane) {
;   const int nblk = N / 32, kb = item / nblk, nb = item - kb * nblk, k0 = 32 * kb, n0 = 32 * nb;
; #pragma unroll 8
;   for (int i = 0; i < 16; ++i) { const int kk = 2 * i + (lane >> 5); scr[kk * 33 + (lane & 31)] = W[(size_t)(k0 + kk) * N + n0 + (lane & 31)]; }
;   asm volatile("s_waitcnt lgkmcnt(0)" ::: "memory");
;   const int c = lane & 3;
; #pragma unroll
;   for (int j = 0; j < 2; ++j) {
;     const int n = (lane >> 2) + 16 * j; const float* sp = scr + (8 * c) * 33 + n;
; __device__ __forceinline__ void prep_phase(const Params& p, char* lds) {
;     ...
;     for (int i = gt; i < 128 * 124 * 32; i += NGT) {
;       const int c4 = i & 31, w = (i >> 5) % 124, b = i / (124 * 32);
;       const size_t so = ((size_t)b * 128 + w + 4) * 128 + c4 * 4, dof = ((size_t)b * 128 + w) * 128 + c4 * 4;
;       *(f32x4*)(p.out + O_KS + dof) = *(const f32x4*)(ck + so);
;       *(f32x4*)(p.out + O_VS + dof) = *(const f32x4*)(cv + so);
;     }
.Lwin_l5:
	v_mov_b32_e32 v105, s101
	v_mad_u32_u24 v105, v105, 0, v104
	v_and_b32_e32 v103, 31, v105
	v_lshrrev_b32_e32 v102, 5, v105
	v_mul_hi_u32 v101, v102, v100
	v_mul_u32_u24_e32 v107, 0x7c, v101
	v_sub_u32_e32 v102, v102, v107
	v_lshlrev_b32_e32 v103, 4, v103
	v_lshl_add_u32 v103, v102, 9, v103
	v_lshl_add_u32 v107, v101, 16, v103
	v_add_u32_e32 v106, 0x800, v107
	v_mov_b32_e32 v109, s101
	v_mad_u32_u24 v109, v109, 1, v104
	v_and_b32_e32 v103, 31, v109
	v_lshrrev_b32_e32 v102, 5, v109
	v_mul_hi_u32 v101, v102, v100
	v_mul_u32_u24_e32 v111, 0x7c, v101
	v_sub_u32_e32 v102, v102, v111
	v_lshlrev_b32_e32 v103, 4, v103
	v_lshl_add_u32 v103, v102, 9, v103
	v_lshl_add_u32 v111, v101, 16, v103
	v_add_u32_e32 v110, 0x800, v111
	v_mov_b32_e32 v113, s101
	v_mad_u32_u24 v113, v113, 2, v104
	v_and_b32_e32 v103, 31, v113
	v_lshrrev_b32_e32 v102, 5, v113
	v_mul_hi_u32 v101, v102, v100
	v_mul_u32_u24_e32 v115, 0x7c, v101
	v_sub_u32_e32 v102, v102, v115
	v_lshlrev_b32_e32 v103, 4, v103
	v_lshl_add_u32 v103, v102, 9, v103
	v_lshl_add_u32 v115, v101, 16, v103
	v_add_u32_e32 v114, 0x800, v115
	v_mov_b32_e32 v117, s101
	v_mad_u32_u24 v117, v117, 3, v104
	v_and_b32_e32 v103, 31, v117
	v_lshrrev_b32_e32 v102, 5, v117
	v_mul_hi_u32 v101, v102, v100
	v_mul_u32_u24_e32 v119, 0x7c, v101
	v_sub_u32_e32 v102, v102, v119
	v_lshlrev_b32_e32 v103, 4, v103
	v_lshl_add_u32 v103, v102, 9, v103
	v_lshl_add_u32 v119, v101, 16, v103
	v_add_u32_e32 v118, 0x800, v119
	v_mov_b32_e32 v121, s101
	v_mad_u32_u24 v121, v121, 4, v104
	v_and_b32_e32 v103, 31, v121
	v_lshrrev_b32_e32 v102, 5, v121
	v_mul_hi_u32 v101, v102, v100
	v_mul_u32_u24_e32 v123, 0x7c, v101
	v_sub_u32_e32 v102, v102, v123
	v_lshlrev_b32_e32 v103, 4, v103
	v_lshl_add_u32 v103, v102, 9, v103
	v_lshl_add_u32 v123, v101, 16, v103
	v_add_u32_e32 v122, 0x800, v123
	v_mov_b32_e32 v125, s101
	v_mad_u32_u24 v125, v125, 5, v104
	v_and_b32_e32 v103, 31, v125
	v_lshrrev_b32_e32 v102, 5, v125
	v_mul_hi_u32 v101, v102, v100
	v_mul_u32_u24_e32 v127, 0x7c, v101
	v_sub_u32_e32 v102, v102, v127
	v_lshlrev_b32_e32 v103, 4, v103
	v_lshl_add_u32 v103, v102, 9, v103
	v_lshl_add_u32 v127, v101, 16, v103
	v_add_u32_e32 v126, 0x800, v127
	v_cmp_gt_u32_e32 vcc, 0x7c000, v105
	s_and_saveexec_b64 s[10:11], vcc
	global_load_dwordx4 v[132:135], v106, s[12:13]
	global_load_dwordx4 v[136:139], v106, s[14:15]
	s_or_b64 exec, exec, s[10:11]
	v_cmp_gt_u32_e32 vcc, 0x7c000, v109
	s_and_saveexec_b64 s[10:11], vcc
	global_load_dwordx4 v[140:143], v110, s[12:13]
	global_load_dwordx4 v[144:147], v110, s[14:15]
	s_or_b64 exec, exec, s[10:11]
	v_cmp_gt_u32_e32 vcc, 0x7c000, v113
	s_and_saveexec_b64 s[10:11], vcc
	global_load_dwordx4 v[148:151], v114, s[12:13]
	global_load_dwordx4 v[152:155], v114, s[14:15]
	s_or_b64 exec, exec, s[10:11]
	v_cmp_gt_u32_e32 vcc, 0x7c000, v117
	s_and_saveexec_b64 s[10:11], vcc
	global_load_dwordx4 v[156:159], v118, s[12:13]
	global_load_dwordx4 v[160:163], v118, s[14:15]
	s_or_b64 exec, exec, s[10:11]
	v_cmp_gt_u32_e32 vcc, 0x7c000, v121
	s_and_saveexec_b64 s[10:11], vcc
	global_load_dwordx4 v[164:167], v122, s[12:13]
	global_load_dwordx4 v[168:171], v122, s[14:15]
	s_or_b64 exec, exec, s[10:11]
	v_cmp_gt_u32_e32 vcc, 0x7c000, v125
	s_and_saveexec_b64 s[10:11], vcc
	global_load_dwordx4 v[172:175], v126, s[12:13]
	global_load_dwordx4 v[176:179], v126, s[14:15]
	s_or_b64 exec, exec, s[10:11]
	s_waitcnt vmcnt(0)
	v_cmp_gt_u32_e32 vcc, 0x7c000, v105
	s_and_saveexec_b64 s[10:11], vcc
	global_store_dwordx4 v107, v[132:135], s[4:5] sc1
	global_store_dwordx4 v107, v[136:139], s[6:7] sc1
	s_or_b64 exec, exec, s[10:11]
	v_cmp_gt_u32_e32 vcc, 0x7c000, v109
	s_and_saveexec_b64 s[10:11], vcc
	global_store_dwordx4 v111, v[140:143], s[4:5] sc1
	global_store_dwordx4 v111, v[144:147], s[6:7] sc1
	s_or_b64 exec, exec, s[10:11]
	v_cmp_gt_u32_e32 vcc, 0x7c000, v113
	s_and_saveexec_b64 s[10:11], vcc
	global_store_dwordx4 v115, v[148:151], s[4:5] sc1
	global_store_dwordx4 v115, v[152:155], s[6:7] sc1
	s_or_b64 exec, exec, s[10:11]
	v_cmp_gt_u32_e32 vcc, 0x7c000, v117
	s_and_saveexec_b64 s[10:11], vcc
	global_store_dwordx4 v119, v[156:159], s[4:5] sc1
	global_store_dwordx4 v119, v[160:163], s[6:7] sc1
	s_or_b64 exec, exec, s[10:11]
	v_cmp_gt_u32_e32 vcc, 0x7c000, v121
	s_and_saveexec_b64 s[10:11], vcc
	global_store_dwordx4 v123, v[164:167], s[4:5] sc1
	global_store_dwordx4 v123, v[168:171], s[6:7] sc1
	s_or_b64 exec, exec, s[10:11]
	v_cmp_gt_u32_e32 vcc, 0x7c000, v125
	s_and_saveexec_b64 s[10:11], vcc
	global_store_dwordx4 v127, v[172:175], s[4:5] sc1
	global_store_dwordx4 v127, v[176:179], s[6:7] sc1
	s_or_b64 exec, exec, s[10:11]
	v_mov_b32_e32 v103, s101
	v_mad_u32_u24 v104, v103, 6, v104
	v_cmp_gt_u32_e32 vcc, 0x7c000, v104
	s_cbranch_vccnz .Lwin_l5
	v_readlane_b32 s12, v244, 6
	v_readlane_b32 s13, v244, 7
	v_readlane_b32 s14, v244, 2
	v_readlane_b32 s15, v244, 3
	v_readfirstlane_b32 s16, v0
	s_nop 3
	s_lshr_b32 s16, s16, 6
	s_add_u32 s14, s14, 0xdc80000
	s_addc_u32 s15, s15, 0
	s_lshl_b32 s17, s98, 3
	s_add_u32 s17, s17, s16
	s_lshl_b32 s18, s100, 3
	s_mul_i32 s16, s16, 0x2200
	v_and_b32_e32 v100, 63, v0
	v_lshrrev_b32_e32 v101, 5, v100
	v_and_b32_e32 v102, 31, v100
	v_mul_u32_u24_e32 v103, 33, v101
	v_add_u32_e32 v103, v103, v102
	v_lshl_add_u32 v103, v103, 2, s16
	v_and_b32_e32 v108, 3, v100
	v_lshrrev_b32_e32 v109, 2, v100
	v_mul_u32_u24_e32 v104, 0x108, v108
	v_add_u32_e32 v104, v104, v109
	v_lshl_add_u32 v104, v104, 2, s16
	v_lshl_add_u32 v106, v101, 10, v102
	v_lshlrev_b32_e32 v106, 2, v106
	v_bfe_u32 v105, v100, 4, 1
	v_lshlrev_b32_e32 v105, 4, v105
	v_lshl_add_u32 v105, v101, 2, v105
	v_and_b32_e32 v107, 3, v109
	v_add_u32_e32 v105, v105, v107
	v_mul_u32_u24_e32 v105, 0x1600, v105
	v_lshl_add_u32 v105, v108, 4, v105
	v_add_u32_e32 v107, 0xb000, v105
	s_cmpk_lt_u32 s17, 0x580
	s_cbranch_scc0 .Ldn_done
; template <int MODE>
; __device__ __forceinline__ void transpose_item(const float* __restrict__ W, int K, int N, bf16_t* __restrict__ WT, int HH, float* scr, int item, int lane) {
;   const int nblk = N / 32, kb = item / nblk, nb = item - kb * nblk, k0 = 32 * kb, n0 = 32 * nb;
; #pragma unroll 8
;   for (int i = 0; i < 16; ++i) { const int kk = 2 * i + (lane >> 5); scr[kk * 33 + (lane & 31)] = W[(size_t)(k0 + kk) * N + n0 + (lane & 31)]; }
; __device__ __forceinline__ void prep_phase(const Params& p, char* lds) {
;     ...
;     for (int it = gw; it < NIT; it += NGW) {
;       int r = it;
;       if (r < I_IN) { transpose_item<0>(p.in[7], 1024, DIN, (bf16_t*)(ws + OFF_WIN), 0, scr, r, lane); continue; } r -= I_IN;
;       if (r < I_GLU) { transpose_item<1>(p.in[16], 512, 2048, (bf16_t*)(ws + OFF_WGLU), 1024, scr, r, lane); continue; } r -= I_GLU;
;       if (r < I_ATT) { transpose_item<0>(p.in[18], 512, 1024, (bf16_t*)(ws + OFF_WATT), 0, scr, r, lane); continue; } r -= I_ATT;
;       if (r < I_O) { transpose_item<0>(p.in[19], 1024, 1024, (bf16_t*)(ws + OFF_WO), 0, scr, r, lane); continue; } r -= I_O;
;       if (r < I_UP) { transpose_item<1>(p.in[22], 1024, 5632, (bf16_t*)(ws + OFF_WUP), DFF, scr, r, lane); continue; } r -= I_UP;
;       transpose_item<0>(p.in[25], DFF, 1024, (bf16_t*)(ws + OFF_WDN), 0, scr, r, lane);
.Ldn_loop:
	s_lshr_b32 s24, s17, 5
	s_lshl_b32 s24, s24, 1
	s_and_b32 s25, s17, 31
	s_lshl_b32 s22, s24, 17
	s_lshl_b32 s23, s25, 7
	s_add_u32 s22, s22, s23
	s_add_u32 s0, s12, s22
	s_addc_u32 s1, s13, 0
	s_mul_i32 s22, s25, 0x2c000
	s_lshl_b32 s23, s24, 6
	s_add_u32 s22, s22, s23
	s_add_u32 s2, s14, s22
	s_addc_u32 s3, s15, 0
	s_mov_b32 s20, 1
	s_lshr_b32 s24, s17, 5
	s_lshl_b32 s24, s24, 1
	s_add_u32 s24, s24, 1
	s_and_b32 s25, s17, 31
	s_lshl_b32 s22, s24, 17
	s_lshl_b32 s23, s25, 7
	s_add_u32 s22, s22, s23
	s_add_u32 s4, s12, s22
	s_addc_u32 s5, s13, 0
	s_mul_i32 s22, s25, 0x2c000
	s_lshl_b32 s23, s24, 6
	s_add_u32 s22, s22, s23
	s_add_u32 s6, s14, s22
	s_addc_u32 s7, s15, 0
	global_load_dword v110, v106, s[0:1]
	s_add_u32 s0, s0, 0x2000
	s_addc_u32 s1, s1, 0
	global_load_dword v111, v106, s[0:1]
	s_add_u32 s0, s0, 0x2000
	s_addc_u32 s1, s1, 0
	global_load_dword v112, v106, s[0:1]
	s_add_u32 s0, s0, 0x2000
	s_addc_u32 s1, s1, 0
	global_load_dword v113, v106, s[0:1]
	s_add_u32 s0, s0, 0x2000
	s_addc_u32 s1, s1, 0
	global_load_dword v114, v106, s[0:1]
	s_add_u32 s0, s0, 0x2000
	s_addc_u32 s1, s1, 0
	global_load_dword v115, v106, s[0:1]
	s_add_u32 s0, s0, 0x2000
	s_addc_u32 s1, s1, 0
	global_load_dword v116, v106, s[0:1]
	s_add_u32 s0, s0, 0x2000
	s_addc_u32 s1, s1, 0
	global_load_dword v117, v106, s[0:1]
	s_add_u32 s0, s0, 0x2000
	s_addc_u32 s1, s1, 0
	global_load_dword v118, v106, s[0:1]
	s_add_u32 s0, s0, 0x2000
	s_addc_u32 s1, s1, 0
	global_load_dword v119, v106, s[0:1]
	s_add_u32 s0, s0, 0x2000
	s_addc_u32 s1, s1, 0
	global_load_dword v120, v106, s[0:1]
	s_add_u32 s0, s0, 0x2000
	s_addc_u32 s1, s1, 0
	global_load_dword v121, v106, s[0:1]
	s_add_u32 s0, s0, 0x2000
	s_addc_u32 s1, s1, 0
	global_load_dword v122, v106, s[0:1]
	s_add_u32 s0, s0, 0x2000
	s_addc_u32 s1, s1, 0
	global_load_dword v123, v106, s[0:1]
	s_add_u32 s0, s0, 0x2000
	s_addc_u32 s1, s1, 0
	global_load_dword v124, v106, s[0:1]
	s_add_u32 s0, s0, 0x2000
	s_addc_u32 s1, s1, 0
	global_load_dword v125, v106, s[0:1]
	s_cmp_eq_u32 s20, 0
	s_cbranch_scc1 .Ldn_noB1
	global_load_dword v126, v106, s[4:5]
	s_add_u32 s4, s4, 0x2000
	s_addc_u32 s5, s5, 0
	global_load_dword v127, v106, s[4:5]
	s_add_u32 s4, s4, 0x2000
	s_addc_u32 s5, s5, 0
	global_load_dword v128, v106, s[4:5]
	s_add_u32 s4, s4, 0x2000
	s_addc_u32 s5, s5, 0
	global_load_dword v129, v106, s[4:5]
	s_add_u32 s4, s4, 0x2000
	s_addc_u32 s5, s5, 0
	global_load_dword v130, v106, s[4:5]
	s_add_u32 s4, s4, 0x2000
	s_addc_u32 s5, s5, 0
	global_load_dword v131, v106, s[4:5]
	s_add_u32 s4, s4, 0x2000
	s_addc_u32 s5, s5, 0
	global_load_dword v132, v106, s[4:5]
	s_add_u32 s4, s4, 0x2000
	s_addc_u32 s5, s5, 0
	global_load_dword v133, v106, s[4:5]
	s_add_u32 s4, s4, 0x2000
	s_addc_u32 s5, s5, 0
	global_load_dword v134, v106, s[4:5]
	s_add_u32 s4, s4, 0x2000
	s_addc_u32 s5, s5, 0
	global_load_dword v135, v106, s[4:5]
	s_add_u32 s4, s4, 0x2000
	s_addc_u32 s5, s5, 0
	global_load_dword v136, v106, s[4:5]
	s_add_u32 s4, s4, 0x2000
	s_addc_u32 s5, s5, 0
	global_load_dword v137, v106, s[4:5]
	s_add_u32 s4, s4, 0x2000
	s_addc_u32 s5, s5, 0
	global_load_dword v138, v106, s[4:5]
	s_add_u32 s4, s4, 0x2000
	s_addc_u32 s5, s5, 0
	global_load_dword v139, v106, s[4:5]
	s_add_u32 s4, s4, 0x2000
	s_addc_u32 s5, s5, 0
	global_load_dword v140, v106, s[4:5]
	s_add_u32 s4, s4, 0x2000
	s_addc_u32 s5, s5, 0
	global_load_dword v141, v106, s[4:5]
	s_waitcnt vmcnt(16)
	s_branch .Ldn_wA

; __device__ __forceinline__ void prep_phase(const Params& p, char* lds) {
;     ...
;     for (int it = gw; it < NIT; it += NGW) {
;       int r = it;
;       if (r < I_IN) { transpose_item<0>(p.in[7], 1024, DIN, (bf16_t*)(ws + OFF_WIN), 0, scr, r, lane); continue; } r -= I_IN;
;       if (r < I_GLU) { transpose_item<1>(p.in[16], 512, 2048, (bf16_t*)(ws + OFF_WGLU), 1024, scr, r, lane); continue; } r -= I_GLU;
;       if (r < I_ATT) { transpose_item<0>(p.in[18], 512, 1024, (bf16_t*)(ws + OFF_WATT), 0, scr, r, lane); continue; } r -= I_ATT;
;       if (r < I_O) { transpose_item<0>(p.in[19], 1024, 1024, (bf16_t*)(ws + OFF_WO), 0, scr, r, lane); continue; } r -= I_O;
;       if (r < I_UP) { transpose_item<1>(p.in[22], 1024, 5632, (bf16_t*)(ws + OFF_WUP), DFF, scr, r, lane); continue; } r -= I_UP;
;       transpose_item<0>(p.in[25], DFF, 1024, (bf16_t*)(ws + OFF_WDN), 0, scr, r, lane);
.Ldn_noB4:
	s_nop 0
	s_add_u32 s17, s17, s18
	s_cmpk_lt_u32 s17, 0x580
	s_cbranch_scc1 .Ldn_loop

; __device__ __forceinline__ unsigned xb_ld(unsigned* p)              { return __hip_atomic_load(p, __ATOMIC_RELAXED, __HIP_MEMORY_SCOPE_AGENT); }
; __device__ __forceinline__ unsigned xb_add(unsigned* p, unsigned v) { return __hip_atomic_fetch_add(p, v, __ATOMIC_RELAXED, __HIP_MEMORY_SCOPE_AGENT); }
; #define XB_SPIN(cond, bar) do { unsigned _sp = 0; while (cond) { __builtin_amdgcn_s_sleep(1); \
;     if ((++_sp & 255u) == 0u) { if (xb_ld(&(bar)[XB_TMO])) break; if (_sp > XB_SPIN_CAP) { atomicAdd(&(bar)[XB_TMO], 1u); break; } } } } while (0)
;     __device__ __forceinline__ bool next(int i, int& pm, int& pn, int& k0, int& nk, int& slice, int& src) const {
;     ...
;         if (nsplit == 0) return false;
;         int sidx = (int)(L - nwg);
;         if (sidx >= nslice_items) return false;
;         int ncol = nN;
;         if (glu && sidx >= 64) { sidx -= 64; src = 1; ncol = 4; }
;         const int tl = sidx / nsplit; slice = sidx - tl * nsplit; pm = 64 + tl / ncol; pn = tl % ncol; nk = nt / nsplit; k0 = slice * nk; return true;
; __device__ __forceinline__ void xcd_barrier(const XcdBarrier& b) {
;     ...
;             else XB_SPIN(xb_ld(&bar[XB_TOPGEN]) == tg, bar);
;             __builtin_amdgcn_fence(__ATOMIC_ACQUIRE, "agent");
;             xb_add(&bar[XB_XGEN(b.x)], 1u);
;             asm volatile("s_waitcnt vmcnt(0)" ::: "memory");
;         } else {
;             XB_SPIN(xb_ld(&bar[XB_XGEN(b.x)]) == gen, bar);
;             __builtin_amdgcn_fence(__ATOMIC_ACQUIRE, "agent");
;             asm volatile("s_waitcnt vmcnt(0)" ::: "memory");
;         }
;     }
;     __syncthreads();
.Lfb8_spin:
	global_load_dword v4, v1, s[6:7] sc1
	s_waitcnt vmcnt(0)
	v_cmp_ge_u32_e32 vcc, v4, v3
	s_cbranch_vccnz .Lfb8_done
	s_sleep 1
	s_add_u32 s8, s8, 1
	s_cmp_lt_u32 s8, 0x200000
	s_cbranch_scc1 .Lfb8_spin
.Lfb8_done:
	s_waitcnt vmcnt(0)
.LBB0_1216:
	s_or_b64 exec, exec, s[2:3]
	v_readlane_b32 s0, v244, 62
	v_readlane_b32 s1, v244, 63
	s_waitcnt lgkmcnt(0)
	s_barrier
	s_and_b64 vcc, exec, s[0:1]
	v_readfirstlane_b32 s12, v0
	s_cbranch_vccz .LBB0_1219
	v_readlane_b32 s6, v244, 33
	s_cmpk_lt_u32 s6, 0x158
	s_mov_b64 s[10:11], 0
	s_cbranch_scc0 .LBB0_1220
	s_and_b32 s2, s6, 0xff
	s_mulk_i32 s2, 0x75
	s_lshr_b32 s2, s2, 8
	s_add_i32 s3, s6, 0xffffff00
	s_sub_i32 s6, s6, s2
	s_bfe_u32 s6, s6, 0x70001
	s_add_i32 s6, s6, s2
	s_bfe_u32 s2, s6, 0x50003
	s_mul_i32 s2, s2, -11
	s_add_i32 s2, s2, s3
	s_cmp_gt_u32 s3, 43
	s_cselect_b32 s35, 0x41, 64
	s_bfe_u32 s36, s6, 0x20003
	s_lshl_b32 s6, s2, 2
	s_ashr_i32 s7, s6, 31
	s_lshl_b64 s[6:7], s[6:7], 7
	s_mov_b64 s[8:9], -1
	s_mov_b32 s53, 4
	s_and_b64 vcc, exec, s[10:11]
	s_cbranch_vccnz .LBB0_1221
	s_branch .LBB0_1226
